# nt (non-temporal) hint on the FFN-up epilogue stores of ACT (P1/P8)
# baseline (speedup 1.0000x reference)
; #define PG8_LAS __attribute__((address_space(3)))
; __device__ __forceinline__ unsigned cvt_pk_bf16(float lo, float hi) { unsigned r; asm volatile("v_cvt_pk_bf16_f32 %0, %1, %2" : "=v"(r) : "v"(lo), "v"(hi)); return r; }
;     template <class Sched> __device__ __forceinline__ void pre(const Sched& S) const { rs_table((PG8_LAS float*)RS, ssq, S); }
; __device__ __forceinline__ f32x2 swiglu_pk(f32x2 g, f32x2 u, float nrs, float rs2) {
;     const f32x2 t = g * nrs; f32x2 e; e.x = __builtin_amdgcn_exp2f(t.x); e.y = __builtin_amdgcn_exp2f(t.y);
;     const f32x2 d = e + 1.0f; f32x2 r; r.x = __builtin_amdgcn_rcpf(d.x); r.y = __builtin_amdgcn_rcpf(d.y);
;     return (g * u) * (r * rs2);
; }
;     template <class Sched> __device__ __forceinline__ void pre(const Sched& S) const { rs_table((PG8_LAS float*)RS, ssq, S); }
;     __device__ __forceinline__ void operator()(const f32x4 (&acc)[2][2][4][2], const Unit& u, int wr, int wc, int fr, int fq) const {
;         const int row0 = u.pm * BM + wr * 64 + fr, col0 = u.pn * 128 + wc * 32 + 8 * fq;
;         float rsv[2][4]; rows_rstd(RS + ui * 256, wr, fr, rsv); ++ui;
; #pragma unroll
;         for (int ai = 0; ai < 2; ++ai)
; #pragma unroll
;             for (int m = 0; m < 4; ++m) { const int row = row0 + ai * HALF + m * 16; const float rs = rsv[ai][m], nrs = -1.4426950408889634f * rs, rs2 = rs * rs;
;                 const f32x4 g0 = acc[ai][0][m][0], g1 = acc[ai][0][m][1], u0 = acc[ai][1][m][0], u1 = acc[ai][1][m][1];
;                 const f32x2 a = swiglu_pk((f32x2){g0[0], g0[1]}, (f32x2){u0[0], u0[1]}, nrs, rs2), b = swiglu_pk((f32x2){g0[2], g0[3]}, (f32x2){u0[2], u0[3]}, nrs, rs2);
;                 const f32x2 c = swiglu_pk((f32x2){g1[0], g1[1]}, (f32x2){u1[0], u1[1]}, nrs, rs2), d = swiglu_pk((f32x2){g1[2], g1[3]}, (f32x2){u1[2], u1[3]}, nrs, rs2);
;                 u32x4 w; w.x = cvt_pk_bf16(a.x, a.y); w.y = cvt_pk_bf16(b.x, b.y); w.z = cvt_pk_bf16(c.x, c.y); w.w = cvt_pk_bf16(d.x, d.y);
;                 *(u32x4*)(O + (size_t)row * ldo + col0) = w; }
.LBB0_236:
	v_lshl_add_u32 v161, s58, 10, v152
	ds_read2_b32 v[158:159], v161 offset1:16
	v_pk_mul_f32 v[122:123], v[126:127], v[122:123]
	v_pk_mul_f32 v[120:121], v[124:125], v[120:121]
	v_pk_mul_f32 v[114:115], v[118:119], v[114:115]
	v_pk_mul_f32 v[112:113], v[116:117], v[112:113]
	s_waitcnt lgkmcnt(0)
	v_mul_f32_e32 v162, 0xbfb8aa3b, v158
	v_pk_mul_f32 v[144:145], v[124:125], v[162:163] op_sel_hi:[1,0]
	v_pk_mul_f32 v[166:167], v[126:127], v[162:163] op_sel_hi:[1,0]
	v_exp_f32_e32 v164, v144
	v_exp_f32_e32 v165, v145
	v_exp_f32_e32 v166, v166
	v_exp_f32_e32 v167, v167
	v_mul_f32_e32 v158, v158, v158
	v_pk_add_f32 v[164:165], v[164:165], 1.0 op_sel_hi:[1,0]
	v_lshl_or_b32 v160, s57, 7, v153
	v_rcp_f32_e32 v164, v164
	v_rcp_f32_e32 v165, v165
	v_pk_add_f32 v[126:127], v[166:167], 1.0 op_sel_hi:[1,0]
	v_lshl_add_u32 v157, s36, 8, v150
	v_rcp_f32_e32 v126, v126
	v_rcp_f32_e32 v127, v127
	v_pk_mul_f32 v[124:125], v[158:159], v[164:165] op_sel_hi:[0,1]
	v_pk_mul_f32 v[164:165], v[116:117], v[162:163] op_sel_hi:[1,0]
	v_pk_mul_f32 v[120:121], v[120:121], v[124:125]
	v_exp_f32_e32 v164, v164
	v_exp_f32_e32 v165, v165
	v_pk_mul_f32 v[124:125], v[158:159], v[126:127] op_sel_hi:[0,1]
	v_pk_mul_f32 v[126:127], v[118:119], v[162:163] op_sel_hi:[1,0]
	v_pk_mul_f32 v[122:123], v[122:123], v[124:125]
	v_exp_f32_e32 v126, v126
	v_exp_f32_e32 v127, v127
	v_pk_add_f32 v[124:125], v[164:165], 1.0 op_sel_hi:[1,0]
	ds_read2_b32 v[148:149], v161 offset0:32 offset1:48
	ds_read2_b32 v[146:147], v161 offset0:128 offset1:144
	v_rcp_f32_e32 v124, v124
	v_rcp_f32_e32 v125, v125
	v_pk_add_f32 v[118:119], v[126:127], 1.0 op_sel_hi:[1,0]
	ds_read2_b32 v[144:145], v161 offset0:160 offset1:176
	v_rcp_f32_e32 v118, v118
	v_rcp_f32_e32 v119, v119
	v_pk_mul_f32 v[116:117], v[158:159], v[124:125] op_sel_hi:[0,1]
	v_pk_mul_f32 v[112:113], v[112:113], v[116:117]
	v_ashrrev_i32_e32 v161, 31, v160
	v_pk_mul_f32 v[116:117], v[158:159], v[118:119] op_sel_hi:[0,1]
	v_pk_mul_f32 v[114:115], v[114:115], v[116:117]
	v_cvt_pk_bf16_f32 v116, v120, v121
	v_cvt_pk_bf16_f32 v117, v122, v123
	v_cvt_pk_bf16_f32 v118, v112, v113
	v_mov_b64_e32 v[112:113], s[82:83]
	v_cvt_pk_bf16_f32 v119, v114, v115
	v_mad_i64_i32 v[120:121], s[38:39], v157, s55, v[112:113]
	v_lshlrev_b64 v[114:115], 1, v[160:161]
	v_mul_f32_e32 v122, 0xbfb8aa3b, v159
	v_lshl_add_u64 v[120:121], v[120:121], 0, v[114:115]
	v_pk_mul_f32 v[124:125], v[108:109], v[122:123] op_sel_hi:[1,0]
	global_store_dwordx4 v[120:121], v[116:119], off nt
	v_exp_f32_e32 v124, v124
	v_exp_f32_e32 v125, v125
	v_pk_mul_f32 v[120:121], v[110:111], v[122:123] op_sel_hi:[1,0]
	v_pk_mul_f32 v[106:107], v[110:111], v[106:107]
	v_exp_f32_e32 v120, v120
	v_exp_f32_e32 v121, v121
	v_pk_add_f32 v[118:119], v[124:125], 1.0 op_sel_hi:[1,0]
	v_or_b32_e32 v117, 16, v157
	v_rcp_f32_e32 v118, v118
	v_rcp_f32_e32 v119, v119
	v_pk_add_f32 v[110:111], v[120:121], 1.0 op_sel_hi:[1,0]
	v_mul_f32_e32 v116, v159, v159
	v_rcp_f32_e32 v110, v110
	v_rcp_f32_e32 v111, v111
	v_pk_mul_f32 v[104:105], v[108:109], v[104:105]
	v_pk_mul_f32 v[108:109], v[116:117], v[118:119] op_sel_hi:[0,1]
	v_pk_mul_f32 v[118:119], v[100:101], v[122:123] op_sel_hi:[1,0]
	v_pk_mul_f32 v[104:105], v[104:105], v[108:109]
	v_exp_f32_e32 v118, v118
	v_exp_f32_e32 v119, v119
	v_pk_mul_f32 v[108:109], v[116:117], v[110:111] op_sel_hi:[0,1]
	v_pk_mul_f32 v[110:111], v[102:103], v[122:123] op_sel_hi:[1,0]
	v_pk_mul_f32 v[106:107], v[106:107], v[108:109]
	v_exp_f32_e32 v110, v110
	v_exp_f32_e32 v111, v111
	v_pk_add_f32 v[108:109], v[118:119], 1.0 op_sel_hi:[1,0]
	v_pk_mul_f32 v[98:99], v[102:103], v[98:99]
	v_rcp_f32_e32 v108, v108
	v_rcp_f32_e32 v109, v109
	v_pk_add_f32 v[102:103], v[110:111], 1.0 op_sel_hi:[1,0]
	v_pk_mul_f32 v[96:97], v[100:101], v[96:97]
	v_rcp_f32_e32 v102, v102
	v_rcp_f32_e32 v103, v103
	v_pk_mul_f32 v[100:101], v[116:117], v[108:109] op_sel_hi:[0,1]
	v_pk_mul_f32 v[100:101], v[96:97], v[100:101]
	v_pk_mul_f32 v[90:91], v[94:95], v[90:91]
	v_pk_mul_f32 v[96:97], v[116:117], v[102:103] op_sel_hi:[0,1]
	v_pk_mul_f32 v[102:103], v[98:99], v[96:97]
	v_cvt_pk_bf16_f32 v96, v104, v105
	v_cvt_pk_bf16_f32 v97, v106, v107
	v_cvt_pk_bf16_f32 v98, v100, v101
	v_mad_i64_i32 v[100:101], s[38:39], v117, s55, v[112:113]
	v_cvt_pk_bf16_f32 v99, v102, v103
	s_waitcnt lgkmcnt(0)
; #define PG8_LAS __attribute__((address_space(3)))
; __device__ __forceinline__ unsigned cvt_pk_bf16(float lo, float hi) { unsigned r; asm volatile("v_cvt_pk_bf16_f32 %0, %1, %2" : "=v"(r) : "v"(lo), "v"(hi)); return r; }
;     template <class Sched> __device__ __forceinline__ void pre(const Sched& S) const { rs_table((PG8_LAS float*)RS, ssq, S); }
; __device__ __forceinline__ f32x2 swiglu_pk(f32x2 g, f32x2 u, float nrs, float rs2) {
;     const f32x2 t = g * nrs; f32x2 e; e.x = __builtin_amdgcn_exp2f(t.x); e.y = __builtin_amdgcn_exp2f(t.y);
;     const f32x2 d = e + 1.0f; f32x2 r; r.x = __builtin_amdgcn_rcpf(d.x); r.y = __builtin_amdgcn_rcpf(d.y);
;     return (g * u) * (r * rs2);
; }
;     template <class Sched> __device__ __forceinline__ void pre(const Sched& S) const { rs_table((PG8_LAS float*)RS, ssq, S); }
;     __device__ __forceinline__ void operator()(const f32x4 (&acc)[2][2][4][2], const Unit& u, int wr, int wc, int fr, int fq) const {
;         const int row0 = u.pm * BM + wr * 64 + fr, col0 = u.pn * 128 + wc * 32 + 8 * fq;
;         float rsv[2][4]; rows_rstd(RS + ui * 256, wr, fr, rsv); ++ui;
; #pragma unroll
;         for (int ai = 0; ai < 2; ++ai)
; #pragma unroll
;             for (int m = 0; m < 4; ++m) { const int row = row0 + ai * HALF + m * 16; const float rs = rsv[ai][m], nrs = -1.4426950408889634f * rs, rs2 = rs * rs;
;                 const f32x4 g0 = acc[ai][0][m][0], g1 = acc[ai][0][m][1], u0 = acc[ai][1][m][0], u1 = acc[ai][1][m][1];
;                 const f32x2 a = swiglu_pk((f32x2){g0[0], g0[1]}, (f32x2){u0[0], u0[1]}, nrs, rs2), b = swiglu_pk((f32x2){g0[2], g0[3]}, (f32x2){u0[2], u0[3]}, nrs, rs2);
;                 const f32x2 c = swiglu_pk((f32x2){g1[0], g1[1]}, (f32x2){u1[0], u1[1]}, nrs, rs2), d = swiglu_pk((f32x2){g1[2], g1[3]}, (f32x2){u1[2], u1[3]}, nrs, rs2);
;                 u32x4 w; w.x = cvt_pk_bf16(a.x, a.y); w.y = cvt_pk_bf16(b.x, b.y); w.z = cvt_pk_bf16(c.x, c.y); w.w = cvt_pk_bf16(d.x, d.y);
;                 *(u32x4*)(O + (size_t)row * ldo + col0) = w; }
	v_mul_f32_e32 v102, 0xbfb8aa3b, v148
	v_lshl_add_u64 v[100:101], v[100:101], 0, v[114:115]
	v_pk_mul_f32 v[104:105], v[92:93], v[102:103] op_sel_hi:[1,0]
	global_store_dwordx4 v[100:101], v[96:99], off nt
	v_exp_f32_e32 v104, v104
	v_exp_f32_e32 v105, v105
	v_pk_mul_f32 v[100:101], v[94:95], v[102:103] op_sel_hi:[1,0]
	v_or_b32_e32 v97, 32, v157
	v_exp_f32_e32 v100, v100
	v_exp_f32_e32 v101, v101
	v_pk_add_f32 v[98:99], v[104:105], 1.0 op_sel_hi:[1,0]
	v_mul_f32_e32 v96, v148, v148
	v_rcp_f32_e32 v98, v98
	v_rcp_f32_e32 v99, v99
	v_pk_add_f32 v[94:95], v[100:101], 1.0 op_sel_hi:[1,0]
	v_pk_mul_f32 v[88:89], v[92:93], v[88:89]
	v_rcp_f32_e32 v94, v94
	v_rcp_f32_e32 v95, v95
	v_pk_mul_f32 v[92:93], v[96:97], v[98:99] op_sel_hi:[0,1]
	v_pk_mul_f32 v[98:99], v[84:85], v[102:103] op_sel_hi:[1,0]
	v_pk_mul_f32 v[88:89], v[88:89], v[92:93]
	v_exp_f32_e32 v98, v98
	v_exp_f32_e32 v99, v99
	v_pk_mul_f32 v[92:93], v[96:97], v[94:95] op_sel_hi:[0,1]
	v_pk_mul_f32 v[94:95], v[86:87], v[102:103] op_sel_hi:[1,0]
	v_pk_mul_f32 v[90:91], v[90:91], v[92:93]
	v_exp_f32_e32 v94, v94
	v_exp_f32_e32 v95, v95
	v_pk_add_f32 v[92:93], v[98:99], 1.0 op_sel_hi:[1,0]
	v_pk_mul_f32 v[82:83], v[86:87], v[82:83]
	v_rcp_f32_e32 v92, v92
	v_rcp_f32_e32 v93, v93
	v_pk_add_f32 v[86:87], v[94:95], 1.0 op_sel_hi:[1,0]
	v_pk_mul_f32 v[80:81], v[84:85], v[80:81]
	v_rcp_f32_e32 v86, v86
	v_rcp_f32_e32 v87, v87
	v_pk_mul_f32 v[84:85], v[96:97], v[92:93] op_sel_hi:[0,1]
	v_pk_mul_f32 v[84:85], v[80:81], v[84:85]
	v_pk_mul_f32 v[74:75], v[78:79], v[74:75]
	v_pk_mul_f32 v[80:81], v[96:97], v[86:87] op_sel_hi:[0,1]
	v_pk_mul_f32 v[86:87], v[82:83], v[80:81]
	v_cvt_pk_bf16_f32 v80, v88, v89
	v_cvt_pk_bf16_f32 v81, v90, v91
	v_cvt_pk_bf16_f32 v82, v84, v85
	v_mad_i64_i32 v[84:85], s[38:39], v97, s55, v[112:113]
	v_cvt_pk_bf16_f32 v83, v86, v87
	v_mul_f32_e32 v86, 0xbfb8aa3b, v149
	v_lshl_add_u64 v[84:85], v[84:85], 0, v[114:115]
	v_pk_mul_f32 v[88:89], v[76:77], v[86:87] op_sel_hi:[1,0]
	global_store_dwordx4 v[84:85], v[80:83], off nt
	v_exp_f32_e32 v88, v88
	v_exp_f32_e32 v89, v89
	v_pk_mul_f32 v[84:85], v[78:79], v[86:87] op_sel_hi:[1,0]
	v_or_b32_e32 v81, 48, v157
	v_exp_f32_e32 v84, v84
	v_exp_f32_e32 v85, v85
	v_pk_add_f32 v[82:83], v[88:89], 1.0 op_sel_hi:[1,0]
	v_mul_f32_e32 v80, v149, v149
	v_rcp_f32_e32 v82, v82
	v_rcp_f32_e32 v83, v83
	v_pk_add_f32 v[78:79], v[84:85], 1.0 op_sel_hi:[1,0]
	v_pk_mul_f32 v[72:73], v[76:77], v[72:73]
	v_rcp_f32_e32 v78, v78
	v_rcp_f32_e32 v79, v79
	v_pk_mul_f32 v[76:77], v[80:81], v[82:83] op_sel_hi:[0,1]
	v_pk_mul_f32 v[82:83], v[68:69], v[86:87] op_sel_hi:[1,0]
	v_pk_mul_f32 v[72:73], v[72:73], v[76:77]
	v_exp_f32_e32 v82, v82
	v_exp_f32_e32 v83, v83
	v_pk_mul_f32 v[76:77], v[80:81], v[78:79] op_sel_hi:[0,1]
	v_pk_mul_f32 v[78:79], v[70:71], v[86:87] op_sel_hi:[1,0]
	v_pk_mul_f32 v[74:75], v[74:75], v[76:77]
	v_exp_f32_e32 v78, v78
	v_exp_f32_e32 v79, v79
	v_pk_add_f32 v[76:77], v[82:83], 1.0 op_sel_hi:[1,0]
	v_pk_mul_f32 v[66:67], v[70:71], v[66:67]
	v_rcp_f32_e32 v76, v76
	v_rcp_f32_e32 v77, v77
	v_pk_add_f32 v[70:71], v[78:79], 1.0 op_sel_hi:[1,0]
	v_pk_mul_f32 v[64:65], v[68:69], v[64:65]
	v_rcp_f32_e32 v70, v70
	v_rcp_f32_e32 v71, v71
	v_pk_mul_f32 v[68:69], v[80:81], v[76:77] op_sel_hi:[0,1]
	v_pk_mul_f32 v[68:69], v[64:65], v[68:69]
	v_pk_mul_f32 v[58:59], v[62:63], v[58:59]
	v_pk_mul_f32 v[64:65], v[80:81], v[70:71] op_sel_hi:[0,1]
	v_pk_mul_f32 v[70:71], v[66:67], v[64:65]
	v_cvt_pk_bf16_f32 v64, v72, v73
	v_cvt_pk_bf16_f32 v65, v74, v75
	v_cvt_pk_bf16_f32 v66, v68, v69
	v_mad_i64_i32 v[68:69], s[38:39], v81, s55, v[112:113]
	v_cvt_pk_bf16_f32 v67, v70, v71
	v_mul_f32_e32 v70, 0xbfb8aa3b, v146
	v_lshl_add_u64 v[68:69], v[68:69], 0, v[114:115]
	v_pk_mul_f32 v[72:73], v[60:61], v[70:71] op_sel_hi:[1,0]
	global_store_dwordx4 v[68:69], v[64:67], off nt
	v_exp_f32_e32 v72, v72
	v_exp_f32_e32 v73, v73
	v_pk_mul_f32 v[68:69], v[62:63], v[70:71] op_sel_hi:[1,0]
	v_add_u32_e32 v65, 0x80, v157
	v_exp_f32_e32 v68, v68
	v_exp_f32_e32 v69, v69
	v_pk_add_f32 v[66:67], v[72:73], 1.0 op_sel_hi:[1,0]
	v_mul_f32_e32 v64, v146, v146
	v_rcp_f32_e32 v66, v66
	v_rcp_f32_e32 v67, v67
	v_pk_add_f32 v[62:63], v[68:69], 1.0 op_sel_hi:[1,0]
	v_pk_mul_f32 v[56:57], v[60:61], v[56:57]
	v_rcp_f32_e32 v62, v62
	v_rcp_f32_e32 v63, v63
	v_pk_mul_f32 v[60:61], v[64:65], v[66:67] op_sel_hi:[0,1]
	v_pk_mul_f32 v[66:67], v[52:53], v[70:71] op_sel_hi:[1,0]
	v_pk_mul_f32 v[56:57], v[56:57], v[60:61]
	v_exp_f32_e32 v66, v66
	v_exp_f32_e32 v67, v67
	v_pk_mul_f32 v[60:61], v[64:65], v[62:63] op_sel_hi:[0,1]
	v_pk_mul_f32 v[62:63], v[54:55], v[70:71] op_sel_hi:[1,0]
	v_pk_mul_f32 v[58:59], v[58:59], v[60:61]
	v_exp_f32_e32 v62, v62
	v_exp_f32_e32 v63, v63
	v_pk_add_f32 v[60:61], v[66:67], 1.0 op_sel_hi:[1,0]
	v_pk_mul_f32 v[50:51], v[54:55], v[50:51]
	v_rcp_f32_e32 v60, v60
	v_rcp_f32_e32 v61, v61
	v_pk_add_f32 v[54:55], v[62:63], 1.0 op_sel_hi:[1,0]
	v_pk_mul_f32 v[48:49], v[52:53], v[48:49]
	v_rcp_f32_e32 v54, v54
	v_rcp_f32_e32 v55, v55
	v_pk_mul_f32 v[52:53], v[64:65], v[60:61] op_sel_hi:[0,1]
	v_pk_mul_f32 v[52:53], v[48:49], v[52:53]
	v_pk_mul_f32 v[42:43], v[46:47], v[42:43]
	v_pk_mul_f32 v[48:49], v[64:65], v[54:55] op_sel_hi:[0,1]
	v_pk_mul_f32 v[54:55], v[50:51], v[48:49]
	v_cvt_pk_bf16_f32 v48, v56, v57
	v_cvt_pk_bf16_f32 v49, v58, v59
	v_cvt_pk_bf16_f32 v50, v52, v53
	v_mad_i64_i32 v[52:53], s[38:39], v65, s55, v[112:113]
	v_cvt_pk_bf16_f32 v51, v54, v55
	v_mul_f32_e32 v54, 0xbfb8aa3b, v147
	v_lshl_add_u64 v[52:53], v[52:53], 0, v[114:115]
; #define PG8_LAS __attribute__((address_space(3)))
; __device__ __forceinline__ unsigned cvt_pk_bf16(float lo, float hi) { unsigned r; asm volatile("v_cvt_pk_bf16_f32 %0, %1, %2" : "=v"(r) : "v"(lo), "v"(hi)); return r; }
;     template <class Sched> __device__ __forceinline__ void pre(const Sched& S) const { rs_table((PG8_LAS float*)RS, ssq, S); }
; __device__ __forceinline__ f32x2 swiglu_pk(f32x2 g, f32x2 u, float nrs, float rs2) {
;     const f32x2 t = g * nrs; f32x2 e; e.x = __builtin_amdgcn_exp2f(t.x); e.y = __builtin_amdgcn_exp2f(t.y);
;     const f32x2 d = e + 1.0f; f32x2 r; r.x = __builtin_amdgcn_rcpf(d.x); r.y = __builtin_amdgcn_rcpf(d.y);
;     return (g * u) * (r * rs2);
; }
;     template <class Sched> __device__ __forceinline__ void pre(const Sched& S) const { rs_table((PG8_LAS float*)RS, ssq, S); }
;     __device__ __forceinline__ void operator()(const f32x4 (&acc)[2][2][4][2], const Unit& u, int wr, int wc, int fr, int fq) const {
;         const int row0 = u.pm * BM + wr * 64 + fr, col0 = u.pn * 128 + wc * 32 + 8 * fq;
;         float rsv[2][4]; rows_rstd(RS + ui * 256, wr, fr, rsv); ++ui;
; #pragma unroll
;         for (int ai = 0; ai < 2; ++ai)
; #pragma unroll
;             for (int m = 0; m < 4; ++m) { const int row = row0 + ai * HALF + m * 16; const float rs = rsv[ai][m], nrs = -1.4426950408889634f * rs, rs2 = rs * rs;
;                 const f32x4 g0 = acc[ai][0][m][0], g1 = acc[ai][0][m][1], u0 = acc[ai][1][m][0], u1 = acc[ai][1][m][1];
;                 const f32x2 a = swiglu_pk((f32x2){g0[0], g0[1]}, (f32x2){u0[0], u0[1]}, nrs, rs2), b = swiglu_pk((f32x2){g0[2], g0[3]}, (f32x2){u0[2], u0[3]}, nrs, rs2);
;                 const f32x2 c = swiglu_pk((f32x2){g1[0], g1[1]}, (f32x2){u1[0], u1[1]}, nrs, rs2), d = swiglu_pk((f32x2){g1[2], g1[3]}, (f32x2){u1[2], u1[3]}, nrs, rs2);
;                 u32x4 w; w.x = cvt_pk_bf16(a.x, a.y); w.y = cvt_pk_bf16(b.x, b.y); w.z = cvt_pk_bf16(c.x, c.y); w.w = cvt_pk_bf16(d.x, d.y);
;                 *(u32x4*)(O + (size_t)row * ldo + col0) = w; }
	v_pk_mul_f32 v[56:57], v[44:45], v[54:55] op_sel_hi:[1,0]
	global_store_dwordx4 v[52:53], v[48:51], off nt
	v_exp_f32_e32 v56, v56
	v_exp_f32_e32 v57, v57
	v_pk_mul_f32 v[52:53], v[46:47], v[54:55] op_sel_hi:[1,0]
	v_add_u32_e32 v49, 0x90, v157
	v_exp_f32_e32 v52, v52
	v_exp_f32_e32 v53, v53
	v_pk_add_f32 v[50:51], v[56:57], 1.0 op_sel_hi:[1,0]
	v_mul_f32_e32 v48, v147, v147
	v_rcp_f32_e32 v50, v50
	v_rcp_f32_e32 v51, v51
	v_pk_add_f32 v[46:47], v[52:53], 1.0 op_sel_hi:[1,0]
	v_pk_mul_f32 v[40:41], v[44:45], v[40:41]
	v_rcp_f32_e32 v46, v46
	v_rcp_f32_e32 v47, v47
	v_pk_mul_f32 v[44:45], v[48:49], v[50:51] op_sel_hi:[0,1]
	v_pk_mul_f32 v[50:51], v[36:37], v[54:55] op_sel_hi:[1,0]
	v_pk_mul_f32 v[40:41], v[40:41], v[44:45]
	v_exp_f32_e32 v50, v50
	v_exp_f32_e32 v51, v51
	v_pk_mul_f32 v[44:45], v[48:49], v[46:47] op_sel_hi:[0,1]
	v_pk_mul_f32 v[46:47], v[38:39], v[54:55] op_sel_hi:[1,0]
	v_pk_mul_f32 v[42:43], v[42:43], v[44:45]
	v_exp_f32_e32 v46, v46
	v_exp_f32_e32 v47, v47
	v_pk_add_f32 v[44:45], v[50:51], 1.0 op_sel_hi:[1,0]
	v_pk_mul_f32 v[34:35], v[38:39], v[34:35]
	v_rcp_f32_e32 v44, v44
	v_rcp_f32_e32 v45, v45
	v_pk_add_f32 v[38:39], v[46:47], 1.0 op_sel_hi:[1,0]
	v_pk_mul_f32 v[32:33], v[36:37], v[32:33]
	v_rcp_f32_e32 v38, v38
	v_rcp_f32_e32 v39, v39
	v_pk_mul_f32 v[36:37], v[48:49], v[44:45] op_sel_hi:[0,1]
	v_pk_mul_f32 v[36:37], v[32:33], v[36:37]
	v_pk_mul_f32 v[26:27], v[30:31], v[26:27]
	v_pk_mul_f32 v[32:33], v[48:49], v[38:39] op_sel_hi:[0,1]
	v_pk_mul_f32 v[38:39], v[34:35], v[32:33]
	v_cvt_pk_bf16_f32 v32, v40, v41
	v_cvt_pk_bf16_f32 v33, v42, v43
	v_cvt_pk_bf16_f32 v34, v36, v37
	v_mad_i64_i32 v[36:37], s[38:39], v49, s55, v[112:113]
	v_cvt_pk_bf16_f32 v35, v38, v39
	v_mul_f32_e32 v38, 0xbfb8aa3b, v144
	v_lshl_add_u64 v[36:37], v[36:37], 0, v[114:115]
	v_pk_mul_f32 v[40:41], v[28:29], v[38:39] op_sel_hi:[1,0]
	global_store_dwordx4 v[36:37], v[32:35], off nt
	v_exp_f32_e32 v40, v40
	v_exp_f32_e32 v41, v41
	v_pk_mul_f32 v[36:37], v[30:31], v[38:39] op_sel_hi:[1,0]
	v_add_u32_e32 v33, 0xa0, v157
	v_exp_f32_e32 v36, v36
	v_exp_f32_e32 v37, v37
	v_pk_add_f32 v[34:35], v[40:41], 1.0 op_sel_hi:[1,0]
	v_mul_f32_e32 v32, v144, v144
	v_rcp_f32_e32 v34, v34
	v_rcp_f32_e32 v35, v35
	v_pk_add_f32 v[30:31], v[36:37], 1.0 op_sel_hi:[1,0]
	v_pk_mul_f32 v[24:25], v[28:29], v[24:25]
	v_rcp_f32_e32 v30, v30
	v_rcp_f32_e32 v31, v31
	v_pk_mul_f32 v[28:29], v[32:33], v[34:35] op_sel_hi:[0,1]
	v_pk_mul_f32 v[34:35], v[20:21], v[38:39] op_sel_hi:[1,0]
	v_pk_mul_f32 v[24:25], v[24:25], v[28:29]
	v_exp_f32_e32 v34, v34
	v_exp_f32_e32 v35, v35
	v_pk_mul_f32 v[28:29], v[32:33], v[30:31] op_sel_hi:[0,1]
	v_pk_mul_f32 v[30:31], v[22:23], v[38:39] op_sel_hi:[1,0]
	v_pk_mul_f32 v[26:27], v[26:27], v[28:29]
	v_exp_f32_e32 v30, v30
	v_exp_f32_e32 v31, v31
	v_pk_add_f32 v[28:29], v[34:35], 1.0 op_sel_hi:[1,0]
	v_pk_mul_f32 v[18:19], v[22:23], v[18:19]
	v_rcp_f32_e32 v28, v28
	v_rcp_f32_e32 v29, v29
	v_pk_add_f32 v[22:23], v[30:31], 1.0 op_sel_hi:[1,0]
	v_pk_mul_f32 v[16:17], v[20:21], v[16:17]
	v_rcp_f32_e32 v22, v22
	v_rcp_f32_e32 v23, v23
	v_pk_mul_f32 v[20:21], v[32:33], v[28:29] op_sel_hi:[0,1]
	v_pk_mul_f32 v[20:21], v[16:17], v[20:21]
	v_pk_mul_f32 v[10:11], v[14:15], v[10:11]
	v_pk_mul_f32 v[16:17], v[32:33], v[22:23] op_sel_hi:[0,1]
	v_pk_mul_f32 v[22:23], v[18:19], v[16:17]
	v_cvt_pk_bf16_f32 v16, v24, v25
	v_cvt_pk_bf16_f32 v17, v26, v27
	v_cvt_pk_bf16_f32 v18, v20, v21
	v_mad_i64_i32 v[20:21], s[38:39], v33, s55, v[112:113]
	v_cvt_pk_bf16_f32 v19, v22, v23
	v_mul_f32_e32 v22, 0xbfb8aa3b, v145
	v_lshl_add_u64 v[20:21], v[20:21], 0, v[114:115]
	v_pk_mul_f32 v[24:25], v[12:13], v[22:23] op_sel_hi:[1,0]
	global_store_dwordx4 v[20:21], v[16:19], off nt
	v_exp_f32_e32 v24, v24
	v_exp_f32_e32 v25, v25
	v_pk_mul_f32 v[20:21], v[14:15], v[22:23] op_sel_hi:[1,0]
	v_add_u32_e32 v17, 0xb0, v157
	v_exp_f32_e32 v20, v20
	v_exp_f32_e32 v21, v21
	v_pk_add_f32 v[18:19], v[24:25], 1.0 op_sel_hi:[1,0]
	v_mul_f32_e32 v16, v145, v145
	v_rcp_f32_e32 v18, v18
	v_rcp_f32_e32 v19, v19
	v_pk_add_f32 v[14:15], v[20:21], 1.0 op_sel_hi:[1,0]
	v_pk_mul_f32 v[8:9], v[12:13], v[8:9]
	v_rcp_f32_e32 v14, v14
	v_rcp_f32_e32 v15, v15
	v_pk_mul_f32 v[12:13], v[16:17], v[18:19] op_sel_hi:[0,1]
	v_pk_mul_f32 v[18:19], v[4:5], v[22:23] op_sel_hi:[1,0]
	v_pk_mul_f32 v[8:9], v[8:9], v[12:13]
	v_exp_f32_e32 v18, v18
	v_exp_f32_e32 v19, v19
	v_pk_mul_f32 v[12:13], v[16:17], v[14:15] op_sel_hi:[0,1]
	v_pk_mul_f32 v[14:15], v[6:7], v[22:23] op_sel_hi:[1,0]
	v_pk_mul_f32 v[10:11], v[10:11], v[12:13]
	v_exp_f32_e32 v14, v14
	v_exp_f32_e32 v15, v15
	v_pk_add_f32 v[12:13], v[18:19], 1.0 op_sel_hi:[1,0]
	v_pk_mul_f32 v[2:3], v[6:7], v[2:3]
	v_rcp_f32_e32 v12, v12
	v_rcp_f32_e32 v13, v13
	v_pk_add_f32 v[6:7], v[14:15], 1.0 op_sel_hi:[1,0]
	v_pk_mul_f32 v[0:1], v[4:5], v[0:1]
	v_rcp_f32_e32 v6, v6
	v_rcp_f32_e32 v7, v7
	v_pk_mul_f32 v[4:5], v[16:17], v[12:13] op_sel_hi:[0,1]
	v_pk_mul_f32 v[4:5], v[0:1], v[4:5]
	s_andn2_b64 vcc, exec, s[6:7]
	v_pk_mul_f32 v[0:1], v[16:17], v[6:7] op_sel_hi:[0,1]
	v_pk_mul_f32 v[6:7], v[2:3], v[0:1]
	v_cvt_pk_bf16_f32 v0, v8, v9
	v_cvt_pk_bf16_f32 v1, v10, v11
	v_cvt_pk_bf16_f32 v2, v4, v5
	v_mad_i64_i32 v[4:5], s[38:39], v17, s55, v[112:113]
	v_lshl_add_u64 v[4:5], v[4:5], 0, v[114:115]
	s_mov_b64 s[6:7], -1
	v_cvt_pk_bf16_f32 v3, v6, v7
	global_store_dwordx4 v[4:5], v[0:3], off nt
	s_cbranch_vccnz .LBB0_225
	s_andn2_b64 vcc, exec, s[4:5]
	s_cbranch_vccnz .LBB0_224
	s_barrier
	s_branch .LBB0_224

; #define PG8_LAS __attribute__((address_space(3)))
; __device__ __forceinline__ unsigned cvt_pk_bf16(float lo, float hi) { unsigned r; asm volatile("v_cvt_pk_bf16_f32 %0, %1, %2" : "=v"(r) : "v"(lo), "v"(hi)); return r; }
;     template <class Sched> __device__ __forceinline__ void pre(const Sched& S) const { rs_table((PG8_LAS float*)RS, ssq, S); }
; __device__ __forceinline__ f32x2 swiglu_pk(f32x2 g, f32x2 u, float nrs, float rs2) {
;     const f32x2 t = g * nrs; f32x2 e; e.x = __builtin_amdgcn_exp2f(t.x); e.y = __builtin_amdgcn_exp2f(t.y);
;     const f32x2 d = e + 1.0f; f32x2 r; r.x = __builtin_amdgcn_rcpf(d.x); r.y = __builtin_amdgcn_rcpf(d.y);
;     return (g * u) * (r * rs2);
; }
;     template <class Sched> __device__ __forceinline__ void pre(const Sched& S) const { rs_table((PG8_LAS float*)RS, ssq, S); }
;     __device__ __forceinline__ void operator()(const f32x4 (&acc)[2][2][4][2], const Unit& u, int wr, int wc, int fr, int fq) const {
;         const int row0 = u.pm * BM + wr * 64 + fr, col0 = u.pn * 128 + wc * 32 + 8 * fq;
;         float rsv[2][4]; rows_rstd(RS + ui * 256, wr, fr, rsv); ++ui;
; #pragma unroll
;         for (int ai = 0; ai < 2; ++ai)
; #pragma unroll
;             for (int m = 0; m < 4; ++m) { const int row = row0 + ai * HALF + m * 16; const float rs = rsv[ai][m], nrs = -1.4426950408889634f * rs, rs2 = rs * rs;
;                 const f32x4 g0 = acc[ai][0][m][0], g1 = acc[ai][0][m][1], u0 = acc[ai][1][m][0], u1 = acc[ai][1][m][1];
;                 const f32x2 a = swiglu_pk((f32x2){g0[0], g0[1]}, (f32x2){u0[0], u0[1]}, nrs, rs2), b = swiglu_pk((f32x2){g0[2], g0[3]}, (f32x2){u0[2], u0[3]}, nrs, rs2);
;                 const f32x2 c = swiglu_pk((f32x2){g1[0], g1[1]}, (f32x2){u1[0], u1[1]}, nrs, rs2), d = swiglu_pk((f32x2){g1[2], g1[3]}, (f32x2){u1[2], u1[3]}, nrs, rs2);
;                 u32x4 w; w.x = cvt_pk_bf16(a.x, a.y); w.y = cvt_pk_bf16(b.x, b.y); w.z = cvt_pk_bf16(c.x, c.y); w.w = cvt_pk_bf16(d.x, d.y);
;                 *(u32x4*)(O + (size_t)row * ldo + col0) = w; }
.LBB0_1364:
	v_lshl_add_u32 v161, s47, 10, v152
	ds_read2_b32 v[158:159], v161 offset1:16
	v_pk_mul_f32 v[122:123], v[126:127], v[122:123]
	v_pk_mul_f32 v[120:121], v[124:125], v[120:121]
	v_pk_mul_f32 v[114:115], v[118:119], v[114:115]
	v_pk_mul_f32 v[112:113], v[116:117], v[112:113]
	s_waitcnt lgkmcnt(0)
	v_mul_f32_e32 v162, 0xbfb8aa3b, v158
	v_pk_mul_f32 v[144:145], v[124:125], v[162:163] op_sel_hi:[1,0]
	v_pk_mul_f32 v[166:167], v[126:127], v[162:163] op_sel_hi:[1,0]
	v_exp_f32_e32 v164, v144
	v_exp_f32_e32 v165, v145
	v_exp_f32_e32 v166, v166
	v_exp_f32_e32 v167, v167
	v_mul_f32_e32 v158, v158, v158
	v_pk_add_f32 v[164:165], v[164:165], 1.0 op_sel_hi:[1,0]
	v_lshl_or_b32 v160, s46, 7, v153
	v_rcp_f32_e32 v164, v164
	v_rcp_f32_e32 v165, v165
	v_pk_add_f32 v[126:127], v[166:167], 1.0 op_sel_hi:[1,0]
	v_lshl_add_u32 v157, s20, 8, v150
	v_rcp_f32_e32 v126, v126
	v_rcp_f32_e32 v127, v127
	v_pk_mul_f32 v[124:125], v[158:159], v[164:165] op_sel_hi:[0,1]
	v_pk_mul_f32 v[164:165], v[116:117], v[162:163] op_sel_hi:[1,0]
	v_pk_mul_f32 v[120:121], v[120:121], v[124:125]
	v_exp_f32_e32 v164, v164
	v_exp_f32_e32 v165, v165
	v_pk_mul_f32 v[124:125], v[158:159], v[126:127] op_sel_hi:[0,1]
	v_pk_mul_f32 v[126:127], v[118:119], v[162:163] op_sel_hi:[1,0]
	v_pk_mul_f32 v[122:123], v[122:123], v[124:125]
	v_exp_f32_e32 v126, v126
	v_exp_f32_e32 v127, v127
	v_pk_add_f32 v[124:125], v[164:165], 1.0 op_sel_hi:[1,0]
	ds_read2_b32 v[148:149], v161 offset0:32 offset1:48
	ds_read2_b32 v[146:147], v161 offset0:128 offset1:144
	v_rcp_f32_e32 v124, v124
	v_rcp_f32_e32 v125, v125
	v_pk_add_f32 v[118:119], v[126:127], 1.0 op_sel_hi:[1,0]
	ds_read2_b32 v[144:145], v161 offset0:160 offset1:176
	v_rcp_f32_e32 v118, v118
	v_rcp_f32_e32 v119, v119
	v_pk_mul_f32 v[116:117], v[158:159], v[124:125] op_sel_hi:[0,1]
	v_pk_mul_f32 v[112:113], v[112:113], v[116:117]
	v_ashrrev_i32_e32 v161, 31, v160
	v_pk_mul_f32 v[116:117], v[158:159], v[118:119] op_sel_hi:[0,1]
	v_pk_mul_f32 v[114:115], v[114:115], v[116:117]
	v_cvt_pk_bf16_f32 v116, v120, v121
	v_cvt_pk_bf16_f32 v117, v122, v123
	v_cvt_pk_bf16_f32 v118, v112, v113
	v_mov_b64_e32 v[112:113], s[82:83]
	v_cvt_pk_bf16_f32 v119, v114, v115
	v_mad_i64_i32 v[120:121], s[22:23], v157, s44, v[112:113]
	v_lshlrev_b64 v[114:115], 1, v[160:161]
	v_mul_f32_e32 v122, 0xbfb8aa3b, v159
	v_lshl_add_u64 v[120:121], v[120:121], 0, v[114:115]
	v_pk_mul_f32 v[124:125], v[108:109], v[122:123] op_sel_hi:[1,0]
	global_store_dwordx4 v[120:121], v[116:119], off nt
	v_exp_f32_e32 v124, v124
	v_exp_f32_e32 v125, v125
	v_pk_mul_f32 v[120:121], v[110:111], v[122:123] op_sel_hi:[1,0]
	v_pk_mul_f32 v[106:107], v[110:111], v[106:107]
	v_exp_f32_e32 v120, v120
	v_exp_f32_e32 v121, v121
	v_pk_add_f32 v[118:119], v[124:125], 1.0 op_sel_hi:[1,0]
	v_or_b32_e32 v117, 16, v157
	v_rcp_f32_e32 v118, v118
	v_rcp_f32_e32 v119, v119
	v_pk_add_f32 v[110:111], v[120:121], 1.0 op_sel_hi:[1,0]
	v_mul_f32_e32 v116, v159, v159
	v_rcp_f32_e32 v110, v110
	v_rcp_f32_e32 v111, v111
	v_pk_mul_f32 v[104:105], v[108:109], v[104:105]
	v_pk_mul_f32 v[108:109], v[116:117], v[118:119] op_sel_hi:[0,1]
	v_pk_mul_f32 v[118:119], v[100:101], v[122:123] op_sel_hi:[1,0]
	v_pk_mul_f32 v[104:105], v[104:105], v[108:109]
	v_exp_f32_e32 v118, v118
	v_exp_f32_e32 v119, v119
	v_pk_mul_f32 v[108:109], v[116:117], v[110:111] op_sel_hi:[0,1]
	v_pk_mul_f32 v[110:111], v[102:103], v[122:123] op_sel_hi:[1,0]
	v_pk_mul_f32 v[106:107], v[106:107], v[108:109]
	v_exp_f32_e32 v110, v110
	v_exp_f32_e32 v111, v111
	v_pk_add_f32 v[108:109], v[118:119], 1.0 op_sel_hi:[1,0]
	v_pk_mul_f32 v[98:99], v[102:103], v[98:99]
	v_rcp_f32_e32 v108, v108
	v_rcp_f32_e32 v109, v109
	v_pk_add_f32 v[102:103], v[110:111], 1.0 op_sel_hi:[1,0]
	v_pk_mul_f32 v[96:97], v[100:101], v[96:97]
	v_rcp_f32_e32 v102, v102
	v_rcp_f32_e32 v103, v103
	v_pk_mul_f32 v[100:101], v[116:117], v[108:109] op_sel_hi:[0,1]
	v_pk_mul_f32 v[100:101], v[96:97], v[100:101]
	v_pk_mul_f32 v[90:91], v[94:95], v[90:91]
	v_pk_mul_f32 v[96:97], v[116:117], v[102:103] op_sel_hi:[0,1]
	v_pk_mul_f32 v[102:103], v[98:99], v[96:97]
	v_cvt_pk_bf16_f32 v96, v104, v105
	v_cvt_pk_bf16_f32 v97, v106, v107
	v_cvt_pk_bf16_f32 v98, v100, v101
	v_mad_i64_i32 v[100:101], s[22:23], v117, s44, v[112:113]
	v_cvt_pk_bf16_f32 v99, v102, v103
	s_waitcnt lgkmcnt(0)
; __device__ __forceinline__ unsigned cvt_pk_bf16(float lo, float hi) { unsigned r; asm volatile("v_cvt_pk_bf16_f32 %0, %1, %2" : "=v"(r) : "v"(lo), "v"(hi)); return r; }
;     __device__ __forceinline__ void operator()(const f32x4 (&acc)[2][2][4][2], const Unit& u, int wr, int wc, int fr, int fq) const {
;     ...
;             for (int m = 0; m < 4; ++m) { const int row = row0 + ai * HALF + m * 16; const float rs = rsv[ai][m], nrs = -1.4426950408889634f * rs, rs2 = rs * rs;
;                 const f32x4 g0 = acc[ai][0][m][0], g1 = acc[ai][0][m][1], u0 = acc[ai][1][m][0], u1 = acc[ai][1][m][1];
;                 const f32x2 a = swiglu_pk((f32x2){g0[0], g0[1]}, (f32x2){u0[0], u0[1]}, nrs, rs2), b = swiglu_pk((f32x2){g0[2], g0[3]}, (f32x2){u0[2], u0[3]}, nrs, rs2);
;                 const f32x2 c = swiglu_pk((f32x2){g1[0], g1[1]}, (f32x2){u1[0], u1[1]}, nrs, rs2), d = swiglu_pk((f32x2){g1[2], g1[3]}, (f32x2){u1[2], u1[3]}, nrs, rs2);
;                 u32x4 w; w.x = cvt_pk_bf16(a.x, a.y); w.y = cvt_pk_bf16(b.x, b.y); w.z = cvt_pk_bf16(c.x, c.y); w.w = cvt_pk_bf16(d.x, d.y);
;                 *(u32x4*)(O + (size_t)row * ldo + col0) = w; }
	v_mul_f32_e32 v102, 0xbfb8aa3b, v148
	v_lshl_add_u64 v[100:101], v[100:101], 0, v[114:115]
	v_pk_mul_f32 v[104:105], v[92:93], v[102:103] op_sel_hi:[1,0]
	global_store_dwordx4 v[100:101], v[96:99], off nt
	v_exp_f32_e32 v104, v104
	v_exp_f32_e32 v105, v105
	v_pk_mul_f32 v[100:101], v[94:95], v[102:103] op_sel_hi:[1,0]
	v_or_b32_e32 v97, 32, v157
	v_exp_f32_e32 v100, v100
	v_exp_f32_e32 v101, v101
	v_pk_add_f32 v[98:99], v[104:105], 1.0 op_sel_hi:[1,0]
	v_mul_f32_e32 v96, v148, v148
	v_rcp_f32_e32 v98, v98
	v_rcp_f32_e32 v99, v99
	v_pk_add_f32 v[94:95], v[100:101], 1.0 op_sel_hi:[1,0]
	v_pk_mul_f32 v[88:89], v[92:93], v[88:89]
	v_rcp_f32_e32 v94, v94
	v_rcp_f32_e32 v95, v95
	v_pk_mul_f32 v[92:93], v[96:97], v[98:99] op_sel_hi:[0,1]
	v_pk_mul_f32 v[98:99], v[84:85], v[102:103] op_sel_hi:[1,0]
	v_pk_mul_f32 v[88:89], v[88:89], v[92:93]
	v_exp_f32_e32 v98, v98
	v_exp_f32_e32 v99, v99
	v_pk_mul_f32 v[92:93], v[96:97], v[94:95] op_sel_hi:[0,1]
	v_pk_mul_f32 v[94:95], v[86:87], v[102:103] op_sel_hi:[1,0]
	v_pk_mul_f32 v[90:91], v[90:91], v[92:93]
	v_exp_f32_e32 v94, v94
	v_exp_f32_e32 v95, v95
	v_pk_add_f32 v[92:93], v[98:99], 1.0 op_sel_hi:[1,0]
	v_pk_mul_f32 v[82:83], v[86:87], v[82:83]
	v_rcp_f32_e32 v92, v92
	v_rcp_f32_e32 v93, v93
	v_pk_add_f32 v[86:87], v[94:95], 1.0 op_sel_hi:[1,0]
	v_pk_mul_f32 v[80:81], v[84:85], v[80:81]
	v_rcp_f32_e32 v86, v86
	v_rcp_f32_e32 v87, v87
	v_pk_mul_f32 v[84:85], v[96:97], v[92:93] op_sel_hi:[0,1]
	v_pk_mul_f32 v[84:85], v[80:81], v[84:85]
	v_pk_mul_f32 v[74:75], v[78:79], v[74:75]
	v_pk_mul_f32 v[80:81], v[96:97], v[86:87] op_sel_hi:[0,1]
	v_pk_mul_f32 v[86:87], v[82:83], v[80:81]
	v_cvt_pk_bf16_f32 v80, v88, v89
	v_cvt_pk_bf16_f32 v81, v90, v91
	v_cvt_pk_bf16_f32 v82, v84, v85
	v_mad_i64_i32 v[84:85], s[22:23], v97, s44, v[112:113]
	v_cvt_pk_bf16_f32 v83, v86, v87
	v_mul_f32_e32 v86, 0xbfb8aa3b, v149
	v_lshl_add_u64 v[84:85], v[84:85], 0, v[114:115]
	v_pk_mul_f32 v[88:89], v[76:77], v[86:87] op_sel_hi:[1,0]
	global_store_dwordx4 v[84:85], v[80:83], off nt
	v_exp_f32_e32 v88, v88
	v_exp_f32_e32 v89, v89
	v_pk_mul_f32 v[84:85], v[78:79], v[86:87] op_sel_hi:[1,0]
	v_or_b32_e32 v81, 48, v157
	v_exp_f32_e32 v84, v84
	v_exp_f32_e32 v85, v85
	v_pk_add_f32 v[82:83], v[88:89], 1.0 op_sel_hi:[1,0]
	v_mul_f32_e32 v80, v149, v149
	v_rcp_f32_e32 v82, v82
	v_rcp_f32_e32 v83, v83
	v_pk_add_f32 v[78:79], v[84:85], 1.0 op_sel_hi:[1,0]
	v_pk_mul_f32 v[72:73], v[76:77], v[72:73]
	v_rcp_f32_e32 v78, v78
	v_rcp_f32_e32 v79, v79
	v_pk_mul_f32 v[76:77], v[80:81], v[82:83] op_sel_hi:[0,1]
	v_pk_mul_f32 v[82:83], v[68:69], v[86:87] op_sel_hi:[1,0]
	v_pk_mul_f32 v[72:73], v[72:73], v[76:77]
	v_exp_f32_e32 v82, v82
	v_exp_f32_e32 v83, v83
	v_pk_mul_f32 v[76:77], v[80:81], v[78:79] op_sel_hi:[0,1]
	v_pk_mul_f32 v[78:79], v[70:71], v[86:87] op_sel_hi:[1,0]
	v_pk_mul_f32 v[74:75], v[74:75], v[76:77]
	v_exp_f32_e32 v78, v78
	v_exp_f32_e32 v79, v79
	v_pk_add_f32 v[76:77], v[82:83], 1.0 op_sel_hi:[1,0]
	v_pk_mul_f32 v[66:67], v[70:71], v[66:67]
	v_rcp_f32_e32 v76, v76
	v_rcp_f32_e32 v77, v77
	v_pk_add_f32 v[70:71], v[78:79], 1.0 op_sel_hi:[1,0]
	v_pk_mul_f32 v[64:65], v[68:69], v[64:65]
	v_rcp_f32_e32 v70, v70
	v_rcp_f32_e32 v71, v71
	v_pk_mul_f32 v[68:69], v[80:81], v[76:77] op_sel_hi:[0,1]
	v_pk_mul_f32 v[68:69], v[64:65], v[68:69]
	v_pk_mul_f32 v[58:59], v[62:63], v[58:59]
	v_pk_mul_f32 v[64:65], v[80:81], v[70:71] op_sel_hi:[0,1]
	v_pk_mul_f32 v[70:71], v[66:67], v[64:65]
	v_cvt_pk_bf16_f32 v64, v72, v73
	v_cvt_pk_bf16_f32 v65, v74, v75
	v_cvt_pk_bf16_f32 v66, v68, v69
	v_mad_i64_i32 v[68:69], s[22:23], v81, s44, v[112:113]
	v_cvt_pk_bf16_f32 v67, v70, v71
	v_mul_f32_e32 v70, 0xbfb8aa3b, v146
	v_lshl_add_u64 v[68:69], v[68:69], 0, v[114:115]
	v_pk_mul_f32 v[72:73], v[60:61], v[70:71] op_sel_hi:[1,0]
	global_store_dwordx4 v[68:69], v[64:67], off nt
	v_exp_f32_e32 v72, v72
	v_exp_f32_e32 v73, v73
	v_pk_mul_f32 v[68:69], v[62:63], v[70:71] op_sel_hi:[1,0]
	v_add_u32_e32 v65, 0x80, v157
	v_exp_f32_e32 v68, v68
	v_exp_f32_e32 v69, v69
	v_pk_add_f32 v[66:67], v[72:73], 1.0 op_sel_hi:[1,0]
	v_mul_f32_e32 v64, v146, v146
	v_rcp_f32_e32 v66, v66
	v_rcp_f32_e32 v67, v67
	v_pk_add_f32 v[62:63], v[68:69], 1.0 op_sel_hi:[1,0]
	v_pk_mul_f32 v[56:57], v[60:61], v[56:57]
	v_rcp_f32_e32 v62, v62
	v_rcp_f32_e32 v63, v63
	v_pk_mul_f32 v[60:61], v[64:65], v[66:67] op_sel_hi:[0,1]
	v_pk_mul_f32 v[66:67], v[52:53], v[70:71] op_sel_hi:[1,0]
	v_pk_mul_f32 v[56:57], v[56:57], v[60:61]
	v_exp_f32_e32 v66, v66
	v_exp_f32_e32 v67, v67
	v_pk_mul_f32 v[60:61], v[64:65], v[62:63] op_sel_hi:[0,1]
	v_pk_mul_f32 v[62:63], v[54:55], v[70:71] op_sel_hi:[1,0]
	v_pk_mul_f32 v[58:59], v[58:59], v[60:61]
	v_exp_f32_e32 v62, v62
	v_exp_f32_e32 v63, v63
	v_pk_add_f32 v[60:61], v[66:67], 1.0 op_sel_hi:[1,0]
	v_pk_mul_f32 v[50:51], v[54:55], v[50:51]
	v_rcp_f32_e32 v60, v60
	v_rcp_f32_e32 v61, v61
	v_pk_add_f32 v[54:55], v[62:63], 1.0 op_sel_hi:[1,0]
	v_pk_mul_f32 v[48:49], v[52:53], v[48:49]
	v_rcp_f32_e32 v54, v54
	v_rcp_f32_e32 v55, v55
	v_pk_mul_f32 v[52:53], v[64:65], v[60:61] op_sel_hi:[0,1]
	v_pk_mul_f32 v[52:53], v[48:49], v[52:53]
	v_pk_mul_f32 v[42:43], v[46:47], v[42:43]
	v_pk_mul_f32 v[48:49], v[64:65], v[54:55] op_sel_hi:[0,1]
	v_pk_mul_f32 v[54:55], v[50:51], v[48:49]
	v_cvt_pk_bf16_f32 v48, v56, v57
	v_cvt_pk_bf16_f32 v49, v58, v59
	v_cvt_pk_bf16_f32 v50, v52, v53
	v_mad_i64_i32 v[52:53], s[22:23], v65, s44, v[112:113]
	v_cvt_pk_bf16_f32 v51, v54, v55
	v_mul_f32_e32 v54, 0xbfb8aa3b, v147
	v_lshl_add_u64 v[52:53], v[52:53], 0, v[114:115]
; __device__ __forceinline__ unsigned cvt_pk_bf16(float lo, float hi) { unsigned r; asm volatile("v_cvt_pk_bf16_f32 %0, %1, %2" : "=v"(r) : "v"(lo), "v"(hi)); return r; }
;     __device__ __forceinline__ void operator()(const f32x4 (&acc)[2][2][4][2], const Unit& u, int wr, int wc, int fr, int fq) const {
;     ...
;             for (int m = 0; m < 4; ++m) { const int row = row0 + ai * HALF + m * 16; const float rs = rsv[ai][m], nrs = -1.4426950408889634f * rs, rs2 = rs * rs;
;                 const f32x4 g0 = acc[ai][0][m][0], g1 = acc[ai][0][m][1], u0 = acc[ai][1][m][0], u1 = acc[ai][1][m][1];
;                 const f32x2 a = swiglu_pk((f32x2){g0[0], g0[1]}, (f32x2){u0[0], u0[1]}, nrs, rs2), b = swiglu_pk((f32x2){g0[2], g0[3]}, (f32x2){u0[2], u0[3]}, nrs, rs2);
;                 const f32x2 c = swiglu_pk((f32x2){g1[0], g1[1]}, (f32x2){u1[0], u1[1]}, nrs, rs2), d = swiglu_pk((f32x2){g1[2], g1[3]}, (f32x2){u1[2], u1[3]}, nrs, rs2);
;                 u32x4 w; w.x = cvt_pk_bf16(a.x, a.y); w.y = cvt_pk_bf16(b.x, b.y); w.z = cvt_pk_bf16(c.x, c.y); w.w = cvt_pk_bf16(d.x, d.y);
;                 *(u32x4*)(O + (size_t)row * ldo + col0) = w; }
	v_pk_mul_f32 v[56:57], v[44:45], v[54:55] op_sel_hi:[1,0]
	global_store_dwordx4 v[52:53], v[48:51], off nt
	v_exp_f32_e32 v56, v56
	v_exp_f32_e32 v57, v57
	v_pk_mul_f32 v[52:53], v[46:47], v[54:55] op_sel_hi:[1,0]
	v_add_u32_e32 v49, 0x90, v157
	v_exp_f32_e32 v52, v52
	v_exp_f32_e32 v53, v53
	v_pk_add_f32 v[50:51], v[56:57], 1.0 op_sel_hi:[1,0]
	v_mul_f32_e32 v48, v147, v147
	v_rcp_f32_e32 v50, v50
	v_rcp_f32_e32 v51, v51
	v_pk_add_f32 v[46:47], v[52:53], 1.0 op_sel_hi:[1,0]
	v_pk_mul_f32 v[40:41], v[44:45], v[40:41]
	v_rcp_f32_e32 v46, v46
	v_rcp_f32_e32 v47, v47
	v_pk_mul_f32 v[44:45], v[48:49], v[50:51] op_sel_hi:[0,1]
	v_pk_mul_f32 v[50:51], v[36:37], v[54:55] op_sel_hi:[1,0]
	v_pk_mul_f32 v[40:41], v[40:41], v[44:45]
	v_exp_f32_e32 v50, v50
	v_exp_f32_e32 v51, v51
	v_pk_mul_f32 v[44:45], v[48:49], v[46:47] op_sel_hi:[0,1]
	v_pk_mul_f32 v[46:47], v[38:39], v[54:55] op_sel_hi:[1,0]
	v_pk_mul_f32 v[42:43], v[42:43], v[44:45]
	v_exp_f32_e32 v46, v46
	v_exp_f32_e32 v47, v47
	v_pk_add_f32 v[44:45], v[50:51], 1.0 op_sel_hi:[1,0]
	v_pk_mul_f32 v[34:35], v[38:39], v[34:35]
	v_rcp_f32_e32 v44, v44
	v_rcp_f32_e32 v45, v45
	v_pk_add_f32 v[38:39], v[46:47], 1.0 op_sel_hi:[1,0]
	v_pk_mul_f32 v[32:33], v[36:37], v[32:33]
	v_rcp_f32_e32 v38, v38
	v_rcp_f32_e32 v39, v39
	v_pk_mul_f32 v[36:37], v[48:49], v[44:45] op_sel_hi:[0,1]
	v_pk_mul_f32 v[36:37], v[32:33], v[36:37]
	v_pk_mul_f32 v[26:27], v[30:31], v[26:27]
	v_pk_mul_f32 v[32:33], v[48:49], v[38:39] op_sel_hi:[0,1]
	v_pk_mul_f32 v[38:39], v[34:35], v[32:33]
	v_cvt_pk_bf16_f32 v32, v40, v41
	v_cvt_pk_bf16_f32 v33, v42, v43
	v_cvt_pk_bf16_f32 v34, v36, v37
	v_mad_i64_i32 v[36:37], s[22:23], v49, s44, v[112:113]
	v_cvt_pk_bf16_f32 v35, v38, v39
	v_mul_f32_e32 v38, 0xbfb8aa3b, v144
	v_lshl_add_u64 v[36:37], v[36:37], 0, v[114:115]
	v_pk_mul_f32 v[40:41], v[28:29], v[38:39] op_sel_hi:[1,0]
	global_store_dwordx4 v[36:37], v[32:35], off nt
	v_exp_f32_e32 v40, v40
	v_exp_f32_e32 v41, v41
	v_pk_mul_f32 v[36:37], v[30:31], v[38:39] op_sel_hi:[1,0]
	v_add_u32_e32 v33, 0xa0, v157
	v_exp_f32_e32 v36, v36
	v_exp_f32_e32 v37, v37
	v_pk_add_f32 v[34:35], v[40:41], 1.0 op_sel_hi:[1,0]
	v_mul_f32_e32 v32, v144, v144
	v_rcp_f32_e32 v34, v34
	v_rcp_f32_e32 v35, v35
	v_pk_add_f32 v[30:31], v[36:37], 1.0 op_sel_hi:[1,0]
	v_pk_mul_f32 v[24:25], v[28:29], v[24:25]
	v_rcp_f32_e32 v30, v30
	v_rcp_f32_e32 v31, v31
	v_pk_mul_f32 v[28:29], v[32:33], v[34:35] op_sel_hi:[0,1]
	v_pk_mul_f32 v[34:35], v[20:21], v[38:39] op_sel_hi:[1,0]
	v_pk_mul_f32 v[24:25], v[24:25], v[28:29]
	v_exp_f32_e32 v34, v34
	v_exp_f32_e32 v35, v35
	v_pk_mul_f32 v[28:29], v[32:33], v[30:31] op_sel_hi:[0,1]
	v_pk_mul_f32 v[30:31], v[22:23], v[38:39] op_sel_hi:[1,0]
	v_pk_mul_f32 v[26:27], v[26:27], v[28:29]
	v_exp_f32_e32 v30, v30
	v_exp_f32_e32 v31, v31
	v_pk_add_f32 v[28:29], v[34:35], 1.0 op_sel_hi:[1,0]
	v_pk_mul_f32 v[18:19], v[22:23], v[18:19]
	v_rcp_f32_e32 v28, v28
	v_rcp_f32_e32 v29, v29
	v_pk_add_f32 v[22:23], v[30:31], 1.0 op_sel_hi:[1,0]
	v_pk_mul_f32 v[16:17], v[20:21], v[16:17]
	v_rcp_f32_e32 v22, v22
	v_rcp_f32_e32 v23, v23
	v_pk_mul_f32 v[20:21], v[32:33], v[28:29] op_sel_hi:[0,1]
	v_pk_mul_f32 v[20:21], v[16:17], v[20:21]
	v_pk_mul_f32 v[10:11], v[14:15], v[10:11]
	v_pk_mul_f32 v[16:17], v[32:33], v[22:23] op_sel_hi:[0,1]
	v_pk_mul_f32 v[22:23], v[18:19], v[16:17]
	v_cvt_pk_bf16_f32 v16, v24, v25
	v_cvt_pk_bf16_f32 v17, v26, v27
	v_cvt_pk_bf16_f32 v18, v20, v21
	v_mad_i64_i32 v[20:21], s[22:23], v33, s44, v[112:113]
	v_cvt_pk_bf16_f32 v19, v22, v23
	v_mul_f32_e32 v22, 0xbfb8aa3b, v145
	v_lshl_add_u64 v[20:21], v[20:21], 0, v[114:115]
	v_pk_mul_f32 v[24:25], v[12:13], v[22:23] op_sel_hi:[1,0]
	global_store_dwordx4 v[20:21], v[16:19], off nt
	v_exp_f32_e32 v24, v24
	v_exp_f32_e32 v25, v25
	v_pk_mul_f32 v[20:21], v[14:15], v[22:23] op_sel_hi:[1,0]
	v_add_u32_e32 v17, 0xb0, v157
	v_exp_f32_e32 v20, v20
	v_exp_f32_e32 v21, v21
	v_pk_add_f32 v[18:19], v[24:25], 1.0 op_sel_hi:[1,0]
	v_mul_f32_e32 v16, v145, v145
	v_rcp_f32_e32 v18, v18
	v_rcp_f32_e32 v19, v19
	v_pk_add_f32 v[14:15], v[20:21], 1.0 op_sel_hi:[1,0]
	v_pk_mul_f32 v[8:9], v[12:13], v[8:9]
	v_rcp_f32_e32 v14, v14
	v_rcp_f32_e32 v15, v15
	v_pk_mul_f32 v[12:13], v[16:17], v[18:19] op_sel_hi:[0,1]
	v_pk_mul_f32 v[18:19], v[4:5], v[22:23] op_sel_hi:[1,0]
	v_pk_mul_f32 v[8:9], v[8:9], v[12:13]
	v_exp_f32_e32 v18, v18
	v_exp_f32_e32 v19, v19
	v_pk_mul_f32 v[12:13], v[16:17], v[14:15] op_sel_hi:[0,1]
	v_pk_mul_f32 v[14:15], v[6:7], v[22:23] op_sel_hi:[1,0]
	v_pk_mul_f32 v[10:11], v[10:11], v[12:13]
	v_exp_f32_e32 v14, v14
	v_exp_f32_e32 v15, v15
	v_pk_add_f32 v[12:13], v[18:19], 1.0 op_sel_hi:[1,0]
	v_pk_mul_f32 v[2:3], v[6:7], v[2:3]
	v_rcp_f32_e32 v12, v12
	v_rcp_f32_e32 v13, v13
	v_pk_add_f32 v[6:7], v[14:15], 1.0 op_sel_hi:[1,0]
	v_pk_mul_f32 v[0:1], v[4:5], v[0:1]
	v_rcp_f32_e32 v6, v6
	v_rcp_f32_e32 v7, v7
	v_pk_mul_f32 v[4:5], v[16:17], v[12:13] op_sel_hi:[0,1]
	v_pk_mul_f32 v[4:5], v[0:1], v[4:5]
	s_andn2_b64 vcc, exec, s[0:1]
	v_pk_mul_f32 v[0:1], v[16:17], v[6:7] op_sel_hi:[0,1]
	v_pk_mul_f32 v[6:7], v[2:3], v[0:1]
	v_cvt_pk_bf16_f32 v0, v8, v9
	v_cvt_pk_bf16_f32 v1, v10, v11
	v_cvt_pk_bf16_f32 v2, v4, v5
	v_mad_i64_i32 v[4:5], s[22:23], v17, s44, v[112:113]
	v_lshl_add_u64 v[4:5], v[4:5], 0, v[114:115]
	s_mov_b64 s[0:1], -1
	v_cvt_pk_bf16_f32 v3, v6, v7
	global_store_dwordx4 v[4:5], v[0:3], off nt
	s_cbranch_vccnz .LBB0_1357
	s_andn2_b64 vcc, exec, s[4:5]
	s_cbranch_vccnz .LBB0_1356
	s_barrier
	s_branch .LBB0_1356
